# sample attention epilogue: divergent bf16 conv-row loads kept raw and unpacked once per half behind one wait (removes ~24 dependent vmcnt(0) round trips per task)
# baseline (speedup 1.0000x reference)
.LBB0_721:
	s_or_b64 exec, exec, s[12:13]
	global_load_dwordx4 v[104:107], v[106:107], off offset:224
	s_nop 0
	global_load_dwordx4 v[120:123], v118, s[10:11]
	s_nop 0
	global_load_dwordx4 v[116:119], v118, s[6:7]
	s_waitcnt vmcnt(0)
	s_mov_b64 s[14:15], exec
	s_and_b64 exec, s[14:15], s[52:53]
	v_lshlrev_b32_e32 v16, 16, v222
	v_and_b32_e32 v17, 0xffff0000, v222
	v_lshlrev_b32_e32 v18, 16, v223
	v_and_b32_e32 v19, 0xffff0000, v223
	v_lshlrev_b32_e32 v24, 16, v224
	v_and_b32_e32 v25, 0xffff0000, v224
	v_lshlrev_b32_e32 v26, 16, v225
	v_and_b32_e32 v27, 0xffff0000, v225
	v_lshlrev_b32_e32 v44, 16, v226
	v_and_b32_e32 v45, 0xffff0000, v226
	v_lshlrev_b32_e32 v46, 16, v227
	v_and_b32_e32 v47, 0xffff0000, v227
	v_lshlrev_b32_e32 v64, 16, v228
	v_and_b32_e32 v65, 0xffff0000, v228
	v_lshlrev_b32_e32 v66, 16, v229
	v_and_b32_e32 v67, 0xffff0000, v229
	s_andn2_b64 exec, s[14:15], s[54:55]
	v_lshlrev_b32_e32 v20, 16, v230
	v_and_b32_e32 v21, 0xffff0000, v230
	v_lshlrev_b32_e32 v22, 16, v231
	v_and_b32_e32 v23, 0xffff0000, v231
	v_lshlrev_b32_e32 v36, 16, v232
	v_and_b32_e32 v37, 0xffff0000, v232
	v_lshlrev_b32_e32 v38, 16, v233
	v_and_b32_e32 v39, 0xffff0000, v233
	v_lshlrev_b32_e32 v56, 16, v234
	v_and_b32_e32 v57, 0xffff0000, v234
	v_lshlrev_b32_e32 v58, 16, v235
	v_and_b32_e32 v59, 0xffff0000, v235
	v_lshlrev_b32_e32 v76, 16, v236
	v_and_b32_e32 v77, 0xffff0000, v236
	v_lshlrev_b32_e32 v78, 16, v237
	v_and_b32_e32 v79, 0xffff0000, v237
	s_mov_b64 exec, s[14:15]
	v_pk_mul_f32 v[18:19], v[18:19], v[42:43]
	v_pk_mul_f32 v[16:17], v[16:17], v[40:41]
	v_pk_fma_f32 v[18:19], v[22:23], v[34:35], v[18:19]
	v_pk_fma_f32 v[16:17], v[20:21], v[32:33], v[16:17]
	v_lshlrev_b32_e32 v20, 16, v88
	v_and_b32_e32 v21, 0xffff0000, v88
	v_lshlrev_b32_e32 v22, 16, v89
	v_and_b32_e32 v23, 0xffff0000, v89
	v_mov_b32_e32 v101, v100
	v_mov_b32_e32 v144, v100
	v_mov_b32_e32 v145, v100
	s_waitcnt vmcnt(18)
	v_pk_fma_f32 v[18:19], v[30:31], v[22:23], v[18:19]
	v_pk_fma_f32 v[16:17], v[28:29], v[20:21], v[16:17]
	v_lshlrev_b32_e32 v28, 16, v84
	v_and_b32_e32 v29, 0xffff0000, v84
	v_lshlrev_b32_e32 v30, 16, v85
	v_and_b32_e32 v31, 0xffff0000, v85
	v_pk_mul_f32 v[2:3], v[144:145], v[2:3]
	v_pk_mul_f32 v[0:1], v[100:101], v[0:1]
	v_lshlrev_b32_e32 v20, 16, v86
	v_and_b32_e32 v21, 0xffff0000, v86
	v_lshlrev_b32_e32 v22, 16, v87
	v_and_b32_e32 v23, 0xffff0000, v87
	v_pk_mul_f32 v[16:17], v[16:17], v[28:29]
	v_pk_mul_f32 v[18:19], v[18:19], v[30:31]
	v_pk_fma_f32 v[0:1], v[0:1], v[20:21], v[16:17]
	v_pk_fma_f32 v[2:3], v[2:3], v[22:23], v[18:19]
	v_cvt_pk_bf16_f32 v0, v0, v1
	v_cvt_pk_bf16_f32 v1, v2, v3
	global_store_dwordx2 v[108:109], v[0:1], off offset:64
	v_pk_mul_f32 v[0:1], v[144:145], v[6:7]
	v_pk_mul_f32 v[2:3], v[100:101], v[4:5]
	s_waitcnt vmcnt(14)
	v_pk_mul_f32 v[4:5], v[26:27], v[62:63]
	v_pk_mul_f32 v[6:7], v[24:25], v[60:61]
	v_pk_fma_f32 v[4:5], v[38:39], v[54:55], v[4:5]
	v_pk_fma_f32 v[6:7], v[36:37], v[52:53], v[6:7]
	v_lshlrev_b32_e32 v16, 16, v94
	v_and_b32_e32 v17, 0xffff0000, v94
	v_lshlrev_b32_e32 v18, 16, v95
	v_and_b32_e32 v19, 0xffff0000, v95
	s_waitcnt vmcnt(13)
	v_pk_fma_f32 v[4:5], v[50:51], v[18:19], v[4:5]
	v_pk_fma_f32 v[6:7], v[48:49], v[16:17], v[6:7]
	v_lshlrev_b32_e32 v20, 16, v90
	v_and_b32_e32 v21, 0xffff0000, v90
	v_lshlrev_b32_e32 v22, 16, v91
	v_and_b32_e32 v23, 0xffff0000, v91
	v_lshlrev_b32_e32 v16, 16, v92
	v_and_b32_e32 v17, 0xffff0000, v92
	v_lshlrev_b32_e32 v18, 16, v93
	v_and_b32_e32 v19, 0xffff0000, v93
	v_pk_mul_f32 v[6:7], v[6:7], v[20:21]
	v_pk_mul_f32 v[4:5], v[4:5], v[22:23]
	v_pk_fma_f32 v[2:3], v[2:3], v[16:17], v[6:7]
	v_pk_fma_f32 v[0:1], v[0:1], v[18:19], v[4:5]
	v_cvt_pk_bf16_f32 v2, v2, v3
	v_cvt_pk_bf16_f32 v3, v0, v1
	s_waitcnt vmcnt(8)
	v_pk_mul_f32 v[4:5], v[46:47], v[82:83]
	v_pk_mul_f32 v[6:7], v[44:45], v[80:81]
	global_store_dwordx2 v[108:109], v[2:3], off offset:80
	v_pk_mul_f32 v[0:1], v[144:145], v[10:11]
	v_pk_mul_f32 v[2:3], v[100:101], v[8:9]
	v_pk_fma_f32 v[4:5], v[58:59], v[74:75], v[4:5]
	v_pk_fma_f32 v[6:7], v[56:57], v[72:73], v[6:7]
	v_lshlrev_b32_e32 v8, 16, v110
	v_and_b32_e32 v9, 0xffff0000, v110
	v_lshlrev_b32_e32 v10, 16, v111
	v_and_b32_e32 v11, 0xffff0000, v111
	s_waitcnt vmcnt(8)
	v_pk_fma_f32 v[4:5], v[70:71], v[10:11], v[4:5]
	v_pk_fma_f32 v[6:7], v[68:69], v[8:9], v[6:7]
	v_lshlrev_b32_e32 v16, 16, v96
	v_and_b32_e32 v17, 0xffff0000, v96
	v_lshlrev_b32_e32 v18, 16, v97
	v_and_b32_e32 v19, 0xffff0000, v97
	v_lshlrev_b32_e32 v8, 16, v98
	v_and_b32_e32 v9, 0xffff0000, v98
	v_lshlrev_b32_e32 v10, 16, v99
	v_and_b32_e32 v11, 0xffff0000, v99
	v_pk_mul_f32 v[6:7], v[6:7], v[16:17]
	v_pk_mul_f32 v[4:5], v[4:5], v[18:19]
	v_pk_fma_f32 v[2:3], v[2:3], v[8:9], v[6:7]
	v_pk_fma_f32 v[0:1], v[0:1], v[10:11], v[4:5]
	s_waitcnt vmcnt(3)
	v_pk_mul_f32 v[4:5], v[66:67], v[122:123]
	v_pk_mul_f32 v[6:7], v[64:65], v[120:121]
	v_cvt_pk_bf16_f32 v2, v2, v3
	v_cvt_pk_bf16_f32 v3, v0, v1
	v_pk_fma_f32 v[4:5], v[78:79], v[106:107], v[4:5]
	v_pk_fma_f32 v[6:7], v[76:77], v[104:105], v[6:7]
	v_lshlrev_b32_e32 v8, 16, v114
	v_and_b32_e32 v9, 0xffff0000, v114
	v_lshlrev_b32_e32 v10, 16, v115
	v_and_b32_e32 v11, 0xffff0000, v115
	global_store_dwordx2 v[108:109], v[2:3], off offset:96
	v_pk_mul_f32 v[0:1], v[144:145], v[14:15]
	v_pk_mul_f32 v[2:3], v[100:101], v[12:13]
	s_waitcnt vmcnt(3)
	v_pk_fma_f32 v[4:5], v[118:119], v[10:11], v[4:5]
	v_pk_fma_f32 v[6:7], v[116:117], v[8:9], v[6:7]
	v_lshlrev_b32_e32 v12, 16, v102
	v_and_b32_e32 v13, 0xffff0000, v102
	v_lshlrev_b32_e32 v14, 16, v103
	v_and_b32_e32 v15, 0xffff0000, v103
	v_lshlrev_b32_e32 v8, 16, v112
	v_and_b32_e32 v9, 0xffff0000, v112
	v_lshlrev_b32_e32 v10, 16, v113
	v_and_b32_e32 v11, 0xffff0000, v113
	v_pk_mul_f32 v[4:5], v[4:5], v[14:15]
	v_pk_mul_f32 v[6:7], v[6:7], v[12:13]
	v_pk_fma_f32 v[0:1], v[0:1], v[10:11], v[4:5]
	v_pk_fma_f32 v[2:3], v[2:3], v[8:9], v[6:7]
	s_nop 0
	v_cvt_pk_bf16_f32 v2, v2, v3
	v_cvt_pk_bf16_f32 v3, v0, v1
	global_store_dwordx2 v[108:109], v[2:3], off offset:112

.LBB0_744:
	s_or_b64 exec, exec, vcc
	v_mov_b32_e32 v35, v34
	s_mov_b32 s93, s92
	s_mov_b32 s94, s92
	s_mov_b32 s95, s92
	v_lshlrev_b32_e32 v40, 6, v103
	v_mfma_f32_32x32x16_bf16 v[0:15], v[32:35], v[36:39], v[0:15]
	v_mov_b64_e32 v[32:33], s[92:93]
	v_mov_b64_e32 v[34:35], s[94:95]
	v_mov_b32_e32 v36, v38
	v_mov_b32_e32 v37, v38
	v_mov_b32_e32 v39, v38
	v_or_b32_e32 v182, v40, v137
	v_lshlrev_b64 v[102:103], 11, v[96:97]
	v_mfma_f32_32x32x16_bf16 v[16:31], v[32:35], v[36:39], v[16:31]
	s_ashr_i32 s13, s12, 31
	v_readlane_b32 s56, v254, 6
	s_lshl_b64 s[12:13], s[12:13], 14
	v_readlane_b32 s64, v254, 14
	v_readlane_b32 s65, v254, 15
	s_add_u32 s94, s64, s12
	s_addc_u32 s95, s65, s13
	v_mfma_f32_32x32x16_bf16 v[0:15], v[32:35], v[36:39], v[0:15]
	v_or_b32_e32 v32, v102, v182
	v_mov_b32_e32 v33, v103
	v_lshlrev_b64 v[32:33], 1, v[32:33]
	v_lshl_add_u64 v[34:35], s[40:41], 0, v[32:33]
	v_lshl_add_u64 v[40:41], s[0:1], 0, v[32:33]
	global_load_dwordx2 v[108:109], v[34:35], off
	global_load_dwordx2 v[112:113], v[40:41], off
	v_lshl_add_u64 v[34:35], s[90:91], 0, v[32:33]
	global_load_dwordx2 v[110:111], v[34:35], off
	s_add_u32 s12, s94, 0x2000
	s_addc_u32 s13, s95, 0
	v_readlane_b32 s57, v254, 7
	v_readlane_b32 s58, v254, 8
	v_readlane_b32 s59, v254, 9
	v_readlane_b32 s60, v254, 10
	v_readlane_b32 s61, v254, 11
	v_readlane_b32 s62, v254, 12
	v_readlane_b32 s63, v254, 13
	v_readlane_b32 s66, v254, 16
	v_readlane_b32 s67, v254, 17
	v_readlane_b32 s68, v254, 18
	v_readlane_b32 s69, v254, 19
	v_readlane_b32 s70, v254, 20
	v_readlane_b32 s71, v254, 21
	s_and_saveexec_b64 s[14:15], s[52:53]
	s_xor_b64 vcc, exec, s[14:15]
	s_cbranch_execz .LBB0_746
	global_load_dwordx2 v[222:223], v[40:41], off offset:-4096



.LBB0_750:
	s_andn2_saveexec_b64 s[94:95], s[94:95]
	s_cbranch_execz .LBB0_752

	v_add_co_u32_e32 v196, vcc, 0xffffe000, v40
	s_nop 1
	v_addc_co_u32_e32 v197, vcc, -1, v41, vcc
	global_load_dwordx2 v[230:231], v[196:197], off


.LBB0_752:
	s_or_b64 exec, exec, s[94:95]
	v_or_b32_e32 v52, 8, v182
	v_readlane_b32 s56, v254, 22
	v_or_b32_e32 v40, v102, v52
	v_mov_b32_e32 v41, v103
	v_readlane_b32 s60, v254, 26
	v_readlane_b32 s61, v254, 27
	v_lshlrev_b64 v[40:41], 1, v[40:41]
	s_nop 3
	global_load_dwordx4 v[48:51], v130, s[60:61]
	global_load_dwordx4 v[56:59], v130, s[10:11]
	global_load_dwordx4 v[44:47], v130, s[6:7]
	v_lshl_add_u64 v[42:43], s[40:41], 0, v[40:41]
	v_lshl_add_u64 v[60:61], s[0:1], 0, v[40:41]
	v_lshl_add_u64 v[54:55], s[90:91], 0, v[40:41]
	global_load_dwordx2 v[116:117], v[42:43], off
	global_load_dwordx2 v[114:115], v[54:55], off
	global_load_dwordx2 v[118:119], v[60:61], off
	v_readlane_b32 s57, v254, 23
	v_readlane_b32 s58, v254, 24
	v_readlane_b32 s59, v254, 25
	v_readlane_b32 s62, v254, 28
	v_readlane_b32 s63, v254, 29
	v_readlane_b32 s64, v254, 30
	v_readlane_b32 s65, v254, 31
	v_readlane_b32 s66, v254, 32
	v_readlane_b32 s67, v254, 33
	v_readlane_b32 s68, v254, 34
	v_readlane_b32 s69, v254, 35
	v_readlane_b32 s70, v254, 36
	v_readlane_b32 s71, v254, 37
	s_and_saveexec_b64 s[14:15], s[52:53]
	s_xor_b64 s[94:95], exec, s[14:15]
	s_cbranch_execz .LBB0_754
	global_load_dwordx2 v[224:225], v[60:61], off offset:-4096


	s_or_saveexec_b64 s[94:95], s[94:95]
	v_lshlrev_b32_e32 v62, 2, v52
	s_xor_b64 exec, exec, s[94:95]
	s_cbranch_execz .LBB0_756
	s_branch .LBB0_755

.LBB0_759:

	v_add_co_u32_e32 v196, vcc, 0xffffe000, v60
	s_nop 1
	v_addc_co_u32_e32 v197, vcc, -1, v61, vcc
	global_load_dwordx2 v[232:233], v[196:197], off


.LBB0_760:
	s_or_b64 exec, exec, s[94:95]
	v_readlane_b32 s56, v254, 22
	v_or_b32_e32 v72, 16, v182
	v_readlane_b32 s60, v254, 26
	v_readlane_b32 s61, v254, 27
	v_or_b32_e32 v60, v102, v72
	v_mov_b32_e32 v61, v103
	v_lshl_add_u64 v[106:107], s[60:61], 0, v[130:131]
	v_lshlrev_b64 v[60:61], 1, v[60:61]
	global_load_dwordx4 v[68:71], v[106:107], off offset:32
	global_load_dwordx4 v[76:79], v62, s[10:11]
	global_load_dwordx4 v[64:67], v62, s[6:7]
	v_lshl_add_u64 v[62:63], s[40:41], 0, v[60:61]
	v_lshl_add_u64 v[80:81], s[0:1], 0, v[60:61]
	v_lshl_add_u64 v[74:75], s[90:91], 0, v[60:61]
	global_load_dwordx2 v[122:123], v[62:63], off
	global_load_dwordx2 v[120:121], v[74:75], off
	global_load_dwordx2 v[144:145], v[80:81], off
	v_readlane_b32 s57, v254, 23
	v_readlane_b32 s58, v254, 24
	v_readlane_b32 s59, v254, 25
	v_readlane_b32 s62, v254, 28
	v_readlane_b32 s63, v254, 29
	v_readlane_b32 s64, v254, 30
	v_readlane_b32 s65, v254, 31
	v_readlane_b32 s66, v254, 32
	v_readlane_b32 s67, v254, 33
	v_readlane_b32 s68, v254, 34
	v_readlane_b32 s69, v254, 35
	v_readlane_b32 s70, v254, 36
	v_readlane_b32 s71, v254, 37
	s_and_saveexec_b64 s[14:15], s[52:53]
	s_xor_b64 s[94:95], exec, s[14:15]
	s_cbranch_execz .LBB0_762
	global_load_dwordx2 v[226:227], v[80:81], off offset:-4096


	s_or_saveexec_b64 s[94:95], s[94:95]
	v_lshlrev_b32_e32 v82, 2, v72
	s_xor_b64 exec, exec, s[94:95]
	s_cbranch_execz .LBB0_764
	s_branch .LBB0_763

.LBB0_767:

	v_add_co_u32_e32 v196, vcc, 0xffffe000, v80
	s_nop 1
	v_addc_co_u32_e32 v197, vcc, -1, v81, vcc
	global_load_dwordx2 v[234:235], v[196:197], off


.LBB0_768:
	s_or_b64 exec, exec, s[94:95]
	v_or_b32_e32 v92, 24, v182
	v_or_b32_e32 v80, v102, v92
	v_mov_b32_e32 v81, v103
	v_lshlrev_b64 v[80:81], 1, v[80:81]
	global_load_dwordx4 v[88:91], v[106:107], off offset:64
	global_load_dwordx4 v[96:99], v82, s[10:11]
	global_load_dwordx4 v[84:87], v82, s[6:7]
	v_lshl_add_u64 v[82:83], s[40:41], 0, v[80:81]
	v_lshl_add_u64 v[152:153], s[0:1], 0, v[80:81]
	v_lshl_add_u64 v[94:95], s[90:91], 0, v[80:81]
	global_load_dwordx2 v[148:149], v[82:83], off
	global_load_dwordx2 v[146:147], v[94:95], off
	global_load_dwordx2 v[150:151], v[152:153], off
	s_and_saveexec_b64 s[14:15], s[52:53]
	s_xor_b64 s[94:95], exec, s[14:15]
	s_cbranch_execz .LBB0_770
	global_load_dwordx2 v[228:229], v[152:153], off offset:-4096


	s_or_saveexec_b64 s[94:95], s[94:95]
	v_lshlrev_b32_e32 v143, 2, v92
	s_xor_b64 exec, exec, s[94:95]
	s_cbranch_execz .LBB0_772
	s_branch .LBB0_771

.LBB0_775:

	v_add_co_u32_e32 v196, vcc, 0xffffe000, v152
	s_nop 1
	v_addc_co_u32_e32 v197, vcc, -1, v153, vcc
	global_load_dwordx2 v[236:237], v[196:197], off


.LBB0_776:
	s_or_b64 exec, exec, s[94:95]
	v_sub_f32_e32 v152, v155, v181
	v_exp_f32_e32 v152, v152
	s_waitcnt lgkmcnt(0)
	v_add_f32_e32 v153, v183, v184
	s_waitcnt vmcnt(0)
	s_mov_b64 s[14:15], exec
	s_and_b64 exec, s[14:15], s[52:53]
	v_lshlrev_b32_e32 v32, 16, v222
	v_and_b32_e32 v33, 0xffff0000, v222
	v_lshlrev_b32_e32 v34, 16, v223
	v_and_b32_e32 v35, 0xffff0000, v223
	v_lshlrev_b32_e32 v40, 16, v224
	v_and_b32_e32 v41, 0xffff0000, v224
	v_lshlrev_b32_e32 v42, 16, v225
	v_and_b32_e32 v43, 0xffff0000, v225
	v_lshlrev_b32_e32 v60, 16, v226
	v_and_b32_e32 v61, 0xffff0000, v226
	v_lshlrev_b32_e32 v62, 16, v227
	v_and_b32_e32 v63, 0xffff0000, v227
	v_lshlrev_b32_e32 v80, 16, v228
	v_and_b32_e32 v81, 0xffff0000, v228
	v_lshlrev_b32_e32 v82, 16, v229
	v_and_b32_e32 v83, 0xffff0000, v229
	s_andn2_b64 exec, s[14:15], s[54:55]
	v_lshlrev_b32_e32 v36, 16, v230
	v_and_b32_e32 v37, 0xffff0000, v230
	v_lshlrev_b32_e32 v38, 16, v231
	v_and_b32_e32 v39, 0xffff0000, v231
	v_lshlrev_b32_e32 v52, 16, v232
	v_and_b32_e32 v53, 0xffff0000, v232
	v_lshlrev_b32_e32 v54, 16, v233
	v_and_b32_e32 v55, 0xffff0000, v233
	v_lshlrev_b32_e32 v72, 16, v234
	v_and_b32_e32 v73, 0xffff0000, v234
	v_lshlrev_b32_e32 v74, 16, v235
	v_and_b32_e32 v75, 0xffff0000, v235
	v_lshlrev_b32_e32 v92, 16, v236
	v_and_b32_e32 v93, 0xffff0000, v236
	v_lshlrev_b32_e32 v94, 16, v237
	v_and_b32_e32 v95, 0xffff0000, v237
	s_mov_b64 exec, s[14:15]
	v_pk_mul_f32 v[34:35], v[34:35], v[58:59]
	v_pk_mul_f32 v[32:33], v[32:33], v[56:57]
	v_add_f32_e32 v155, v152, v153
	v_div_scale_f32 v181, s[14:15], v155, v155, 1.0
	v_rcp_f32_e32 v183, v181
	v_readlane_b32 s14, v254, 52
	v_readlane_b32 s15, v254, 53
	v_pk_fma_f32 v[34:35], v[38:39], v[50:51], v[34:35]
	v_pk_fma_f32 v[32:33], v[36:37], v[48:49], v[32:33]
	v_lshl_add_u64 v[152:153], s[14:15], 0, v[100:101]
	v_fma_f32 v101, -v181, v183, 1.0
	v_div_scale_f32 v100, vcc, 1.0, v155, 1.0
	v_fmac_f32_e32 v183, v101, v183
	v_mul_f32_e32 v101, v100, v183
	v_fma_f32 v184, -v181, v101, v100
	v_fmac_f32_e32 v101, v184, v183
	global_load_dwordx4 v[184:187], v[106:107], off offset:96
	global_load_dwordx4 v[188:191], v143, s[10:11]
	global_load_dwordx4 v[192:195], v143, s[6:7]
	v_fma_f32 v100, -v181, v101, v100
	v_div_fmas_f32 v100, v100, v183, v101
	v_lshlrev_b32_e32 v36, 16, v112
	v_and_b32_e32 v37, 0xffff0000, v112
	v_lshlrev_b32_e32 v38, 16, v113
	v_and_b32_e32 v39, 0xffff0000, v113
	v_div_fixup_f32 v100, v100, v155, 1.0
	s_waitcnt vmcnt(18)
	v_pk_fma_f32 v[34:35], v[46:47], v[38:39], v[34:35]
	v_pk_fma_f32 v[32:33], v[44:45], v[36:37], v[32:33]
	v_lshlrev_b32_e32 v44, 16, v110
	v_and_b32_e32 v45, 0xffff0000, v110
	v_lshlrev_b32_e32 v46, 16, v111
	v_and_b32_e32 v47, 0xffff0000, v111
	v_pk_mul_f32 v[16:17], v[100:101], v[16:17] op_sel_hi:[0,1]
	v_pk_mul_f32 v[18:19], v[100:101], v[18:19] op_sel_hi:[0,1]
	v_lshlrev_b32_e32 v36, 16, v108
	v_and_b32_e32 v37, 0xffff0000, v108
	v_lshlrev_b32_e32 v38, 16, v109
	v_and_b32_e32 v39, 0xffff0000, v109
	v_pk_mul_f32 v[32:33], v[32:33], v[44:45]
	v_pk_mul_f32 v[34:35], v[34:35], v[46:47]
	v_pk_fma_f32 v[16:17], v[16:17], v[36:37], v[32:33]
	v_pk_fma_f32 v[18:19], v[18:19], v[38:39], v[34:35]
	v_cvt_pk_bf16_f32 v16, v16, v17
	v_cvt_pk_bf16_f32 v17, v18, v19
	v_lshlrev_b32_e32 v18, 1, v182
	v_mov_b32_e32 v19, v131
	v_lshl_add_u64 v[108:109], v[152:153], 0, v[18:19]
	global_store_dwordx2 v[108:109], v[16:17], off
	v_pk_mul_f32 v[16:17], v[100:101], v[20:21] op_sel_hi:[0,1]
	v_pk_mul_f32 v[18:19], v[100:101], v[22:23] op_sel_hi:[0,1]
	s_waitcnt vmcnt(14)
	v_pk_mul_f32 v[20:21], v[42:43], v[78:79]
	v_pk_mul_f32 v[22:23], v[40:41], v[76:77]
	v_pk_fma_f32 v[20:21], v[54:55], v[70:71], v[20:21]
	v_pk_fma_f32 v[22:23], v[52:53], v[68:69], v[22:23]
	v_lshlrev_b32_e32 v32, 16, v118
	v_and_b32_e32 v33, 0xffff0000, v118
	v_lshlrev_b32_e32 v34, 16, v119
	v_and_b32_e32 v35, 0xffff0000, v119
	s_waitcnt vmcnt(13)
	v_pk_fma_f32 v[20:21], v[66:67], v[34:35], v[20:21]
	v_pk_fma_f32 v[22:23], v[64:65], v[32:33], v[22:23]
	v_lshlrev_b32_e32 v36, 16, v114
	v_and_b32_e32 v37, 0xffff0000, v114
	v_lshlrev_b32_e32 v38, 16, v115
	v_and_b32_e32 v39, 0xffff0000, v115
	v_lshlrev_b32_e32 v32, 16, v116
	v_and_b32_e32 v33, 0xffff0000, v116
	v_lshlrev_b32_e32 v34, 16, v117
	v_and_b32_e32 v35, 0xffff0000, v117
	v_pk_mul_f32 v[22:23], v[22:23], v[36:37]
	v_pk_mul_f32 v[20:21], v[20:21], v[38:39]
	v_pk_fma_f32 v[16:17], v[16:17], v[32:33], v[22:23]
	v_pk_fma_f32 v[18:19], v[18:19], v[34:35], v[20:21]
	v_cvt_pk_bf16_f32 v16, v16, v17
	v_cvt_pk_bf16_f32 v17, v18, v19
	s_waitcnt vmcnt(8)
	v_pk_mul_f32 v[20:21], v[62:63], v[98:99]
	v_pk_mul_f32 v[22:23], v[60:61], v[96:97]
	global_store_dwordx2 v[108:109], v[16:17], off offset:16
	v_pk_mul_f32 v[16:17], v[100:101], v[24:25] op_sel_hi:[0,1]
	v_pk_mul_f32 v[18:19], v[100:101], v[26:27] op_sel_hi:[0,1]
	v_pk_fma_f32 v[20:21], v[74:75], v[90:91], v[20:21]
	v_pk_fma_f32 v[22:23], v[72:73], v[88:89], v[22:23]
	v_lshlrev_b32_e32 v24, 16, v144
	v_and_b32_e32 v25, 0xffff0000, v144
	v_lshlrev_b32_e32 v26, 16, v145
	v_and_b32_e32 v27, 0xffff0000, v145
	s_waitcnt vmcnt(8)
	v_pk_fma_f32 v[20:21], v[86:87], v[26:27], v[20:21]
	v_pk_fma_f32 v[22:23], v[84:85], v[24:25], v[22:23]
	v_lshlrev_b32_e32 v32, 16, v120
	v_and_b32_e32 v33, 0xffff0000, v120
	v_lshlrev_b32_e32 v34, 16, v121
	v_and_b32_e32 v35, 0xffff0000, v121
	v_lshlrev_b32_e32 v24, 16, v122
	v_and_b32_e32 v25, 0xffff0000, v122
	v_lshlrev_b32_e32 v26, 16, v123
	v_and_b32_e32 v27, 0xffff0000, v123
	v_pk_mul_f32 v[22:23], v[22:23], v[32:33]
	v_pk_mul_f32 v[20:21], v[20:21], v[34:35]
	v_pk_fma_f32 v[16:17], v[16:17], v[24:25], v[22:23]
	v_pk_fma_f32 v[18:19], v[18:19], v[26:27], v[20:21]
	s_waitcnt vmcnt(3)
	v_pk_mul_f32 v[20:21], v[82:83], v[190:191]
	v_pk_mul_f32 v[22:23], v[80:81], v[188:189]
	v_cvt_pk_bf16_f32 v16, v16, v17
	v_cvt_pk_bf16_f32 v17, v18, v19
	v_pk_fma_f32 v[20:21], v[94:95], v[186:187], v[20:21]
	v_pk_fma_f32 v[22:23], v[92:93], v[184:185], v[22:23]
	v_lshlrev_b32_e32 v24, 16, v150
	v_and_b32_e32 v25, 0xffff0000, v150
	v_lshlrev_b32_e32 v26, 16, v151
	v_and_b32_e32 v27, 0xffff0000, v151
	global_store_dwordx2 v[108:109], v[16:17], off offset:32
	v_pk_mul_f32 v[16:17], v[100:101], v[28:29] op_sel_hi:[0,1]
	v_pk_mul_f32 v[18:19], v[100:101], v[30:31] op_sel_hi:[0,1]
	s_waitcnt vmcnt(3)
	v_pk_fma_f32 v[20:21], v[194:195], v[26:27], v[20:21]
	v_pk_fma_f32 v[22:23], v[192:193], v[24:25], v[22:23]
	v_lshlrev_b32_e32 v28, 16, v146
	v_and_b32_e32 v29, 0xffff0000, v146
	v_lshlrev_b32_e32 v30, 16, v147
	v_and_b32_e32 v31, 0xffff0000, v147
	v_lshlrev_b32_e32 v24, 16, v148
	v_and_b32_e32 v25, 0xffff0000, v148
	v_lshlrev_b32_e32 v26, 16, v149
	v_and_b32_e32 v27, 0xffff0000, v149
	v_pk_mul_f32 v[20:21], v[20:21], v[30:31]
	v_pk_mul_f32 v[22:23], v[22:23], v[28:29]
	v_pk_fma_f32 v[18:19], v[18:19], v[26:27], v[20:21]
	v_pk_fma_f32 v[16:17], v[16:17], v[24:25], v[22:23]
	v_or_b32_e32 v20, 32, v182
	v_cvt_pk_bf16_f32 v16, v16, v17
	v_cvt_pk_bf16_f32 v17, v18, v19
	global_store_dwordx2 v[108:109], v[16:17], off offset:48
	v_or_b32_e32 v16, v102, v20
	v_mov_b32_e32 v17, v103
	v_lshlrev_b64 v[16:17], 1, v[16:17]
	v_lshl_add_u64 v[18:19], s[40:41], 0, v[16:17]
	v_lshl_add_u64 v[22:23], s[90:91], 0, v[16:17]
	v_lshl_add_u64 v[24:25], s[0:1], 0, v[16:17]
	global_load_dwordx2 v[86:87], v[18:19], off
	global_load_dwordx2 v[84:85], v[22:23], off
	global_load_dwordx2 v[88:89], v[24:25], off
	s_and_saveexec_b64 s[14:15], s[52:53]
	s_xor_b64 s[94:95], exec, s[14:15]
	s_cbranch_execz .LBB0_778
	global_load_dwordx2 v[222:223], v[24:25], off offset:-4096


	s_or_saveexec_b64 s[94:95], s[94:95]
	v_lshlrev_b32_e32 v26, 2, v20
	s_xor_b64 exec, exec, s[94:95]
	s_cbranch_execz .LBB0_780
	s_branch .LBB0_779

.LBB0_783:

	v_add_co_u32_e32 v196, vcc, 0xffffe000, v24
	s_nop 1
	v_addc_co_u32_e32 v197, vcc, -1, v25, vcc
	global_load_dwordx2 v[230:231], v[196:197], off


.LBB0_784:
	s_or_b64 exec, exec, s[94:95]
	v_or_b32_e32 v36, 40, v182
	v_or_b32_e32 v24, v102, v36
	v_mov_b32_e32 v25, v103
	v_lshlrev_b64 v[24:25], 1, v[24:25]
	global_load_dwordx4 v[32:35], v[106:107], off offset:128
	global_load_dwordx4 v[40:43], v26, s[10:11]
	global_load_dwordx4 v[28:31], v26, s[6:7]
	v_lshl_add_u64 v[26:27], s[40:41], 0, v[24:25]
	v_lshl_add_u64 v[44:45], s[0:1], 0, v[24:25]
	v_lshl_add_u64 v[38:39], s[90:91], 0, v[24:25]
	global_load_dwordx2 v[92:93], v[26:27], off
	global_load_dwordx2 v[90:91], v[38:39], off
	global_load_dwordx2 v[94:95], v[44:45], off
	s_and_saveexec_b64 s[14:15], s[52:53]
	s_xor_b64 s[94:95], exec, s[14:15]
	s_cbranch_execz .LBB0_786
	global_load_dwordx2 v[224:225], v[44:45], off offset:-4096


	s_or_saveexec_b64 s[94:95], s[94:95]
	v_lshlrev_b32_e32 v46, 2, v36
	s_xor_b64 exec, exec, s[94:95]
	s_cbranch_execz .LBB0_788
	s_branch .LBB0_787

.LBB0_791:

	v_add_co_u32_e32 v196, vcc, 0xffffe000, v44
	s_nop 1
	v_addc_co_u32_e32 v197, vcc, -1, v45, vcc
	global_load_dwordx2 v[232:233], v[196:197], off


.LBB0_792:
	s_or_b64 exec, exec, s[94:95]
	v_or_b32_e32 v56, 48, v182
	v_or_b32_e32 v44, v102, v56
	v_mov_b32_e32 v45, v103
	v_lshlrev_b64 v[44:45], 1, v[44:45]
	global_load_dwordx4 v[52:55], v[106:107], off offset:160
	global_load_dwordx4 v[60:63], v46, s[10:11]
	global_load_dwordx4 v[48:51], v46, s[6:7]
	v_lshl_add_u64 v[46:47], s[40:41], 0, v[44:45]
	v_lshl_add_u64 v[64:65], s[0:1], 0, v[44:45]
	v_lshl_add_u64 v[58:59], s[90:91], 0, v[44:45]
	global_load_dwordx2 v[98:99], v[46:47], off
	global_load_dwordx2 v[96:97], v[58:59], off
	global_load_dwordx2 v[110:111], v[64:65], off
	s_and_saveexec_b64 s[14:15], s[52:53]
	s_xor_b64 s[94:95], exec, s[14:15]
	s_cbranch_execz .LBB0_794
	global_load_dwordx2 v[226:227], v[64:65], off offset:-4096


	s_or_saveexec_b64 s[94:95], s[94:95]
	v_lshlrev_b32_e32 v66, 2, v56
	s_xor_b64 exec, exec, s[94:95]
	s_cbranch_execz .LBB0_796
	s_branch .LBB0_795

.LBB0_799:

	v_add_co_u32_e32 v196, vcc, 0xffffe000, v64
	s_nop 1
	v_addc_co_u32_e32 v197, vcc, -1, v65, vcc
	global_load_dwordx2 v[234:235], v[196:197], off


.LBB0_800:
	s_or_b64 exec, exec, s[94:95]
	v_or_b32_e32 v76, 56, v182
	v_or_b32_e32 v102, v102, v76
	v_lshlrev_b64 v[64:65], 1, v[102:103]
	global_load_dwordx4 v[72:75], v[106:107], off offset:192
	global_load_dwordx4 v[80:83], v66, s[10:11]
	global_load_dwordx4 v[68:71], v66, s[6:7]
	v_lshl_add_u64 v[66:67], s[40:41], 0, v[64:65]
	v_lshl_add_u64 v[116:117], s[0:1], 0, v[64:65]
	v_lshl_add_u64 v[78:79], s[90:91], 0, v[64:65]
	global_load_dwordx2 v[112:113], v[66:67], off
	global_load_dwordx2 v[102:103], v[78:79], off
	global_load_dwordx2 v[114:115], v[116:117], off
	s_and_saveexec_b64 s[14:15], s[52:53]
	s_xor_b64 s[94:95], exec, s[14:15]
	s_cbranch_execz .LBB0_802
	global_load_dwordx2 v[228:229], v[116:117], off offset:-4096


	s_or_saveexec_b64 s[94:95], s[94:95]
	v_lshlrev_b32_e32 v118, 2, v76
	s_xor_b64 exec, exec, s[94:95]
	s_cbranch_execz .LBB0_804
	s_branch .LBB0_803

.LBB0_807:

	v_add_co_u32_e32 v196, vcc, 0xffffe000, v116
	s_nop 1
	v_addc_co_u32_e32 v197, vcc, -1, v117, vcc
	global_load_dwordx2 v[236:237], v[196:197], off


	s_branch .LBB0_721
